# rspoll: RowStats exchange polls the 4 row slots with one dwordx4 load, two polls in flight staggered by half a round trip, iteration-count give-up bound instead of clock reads (on top of xbpre)
# baseline (speedup 1.0000x reference)
.LBB0_878:
	s_nop 1
	v_mul_f32_e32 v2, v135, v135
	v_mul_f32_e32 v3, v137, v137
	v_fmac_f32_e32 v2, v134, v134
	v_fmac_f32_e32 v3, v136, v136
	v_add_f32_e32 v2, v2, v3
	v_mul_f32_e32 v3, v131, v131
	v_mul_f32_e32 v4, v133, v133
	v_fmac_f32_e32 v3, v130, v130
	v_fmac_f32_e32 v4, v132, v132
	v_add_f32_e32 v3, v3, v4
	v_add_f32_e32 v2, v3, v2
	v_mul_f32_e32 v3, v71, v71
	v_mul_f32_e32 v4, v73, v73
	v_fmac_f32_e32 v3, v70, v70
	v_fmac_f32_e32 v4, v72, v72
	v_add_f32_e32 v3, v3, v4
	v_add_f32_e32 v2, v2, v3
	v_mul_f32_e32 v3, v69, v69
	v_mul_f32_e32 v4, v67, v67
	v_fmac_f32_e32 v3, v68, v68
	v_fmac_f32_e32 v4, v66, v66
	v_add_f32_e32 v3, v3, v4
	v_add_f32_e32 v2, v3, v2
	v_mov_b32_e32 v3, v2
	s_nop 1
	v_permlane16_swap_b32_e32 v2, v3
	v_add_f32_e32 v2, v2, v3
	s_lshl_b32 s6, s45, 2
	v_mov_b32_e32 v3, v2
	v_cmp_gt_u32_e32 vcc, 16, v0
	s_add_i32 s6, s6, 0
	v_permlane32_swap_b32_e32 v2, v3
	s_and_saveexec_b64 s[10:11], vcc
	s_xor_b64 s[10:11], exec, s[10:11]
	s_lshl_b32 s7, s44, 10
	s_add_i32 s7, s6, s7
	v_add_f32_e32 v2, v2, v3
	v_lshl_add_u32 v3, v164, 4, s7
	ds_write_b32 v3, v2
	s_or_b64 exec, exec, s[10:11]
	v_mul_f32_e32 v2, v127, v127
	v_mul_f32_e32 v3, v129, v129
	v_fmac_f32_e32 v2, v126, v126
	v_fmac_f32_e32 v3, v128, v128
	v_add_f32_e32 v2, v2, v3
	v_mul_f32_e32 v3, v123, v123
	v_mul_f32_e32 v4, v125, v125
	v_fmac_f32_e32 v3, v122, v122
	v_fmac_f32_e32 v4, v124, v124
	v_add_f32_e32 v3, v3, v4
	v_add_f32_e32 v2, v3, v2
	v_mul_f32_e32 v3, v63, v63
	v_mul_f32_e32 v4, v65, v65
	v_fmac_f32_e32 v3, v62, v62
	v_fmac_f32_e32 v4, v64, v64
	v_add_f32_e32 v3, v3, v4
	v_add_f32_e32 v2, v2, v3
	v_mul_f32_e32 v3, v59, v59
	v_mul_f32_e32 v4, v61, v61
	v_fmac_f32_e32 v3, v58, v58
	v_fmac_f32_e32 v4, v60, v60
	v_add_f32_e32 v3, v3, v4
	v_add_f32_e32 v2, v3, v2
	v_mov_b32_e32 v3, v2
	s_nop 1
	v_permlane16_swap_b32_e32 v2, v3
	v_add_f32_e32 v2, v2, v3
	v_mov_b32_e32 v3, v2
	s_nop 1
	v_permlane32_swap_b32_e32 v2, v3
	s_and_saveexec_b64 s[10:11], vcc
	s_mov_b32 s45, 0x12000
	s_lshl_b32 s7, s44, 10
	s_add_i32 s7, s6, s7
	v_add_f32_e32 v2, v2, v3
	v_lshl_add_u32 v3, v164, 4, s7
	ds_write_b32 v3, v2 offset:256
	s_or_b64 exec, exec, s[10:11]
	v_mul_f32_e32 v2, v119, v119
	v_mul_f32_e32 v3, v121, v121
	v_fmac_f32_e32 v2, v118, v118
	v_fmac_f32_e32 v3, v120, v120
	v_add_f32_e32 v2, v2, v3
	v_mul_f32_e32 v3, v115, v115
	v_mul_f32_e32 v4, v117, v117
	v_fmac_f32_e32 v3, v114, v114
	v_fmac_f32_e32 v4, v116, v116
	v_add_f32_e32 v3, v3, v4
	v_add_f32_e32 v2, v3, v2
	v_mul_f32_e32 v3, v55, v55
	v_mul_f32_e32 v4, v57, v57
	v_fmac_f32_e32 v3, v54, v54
	v_fmac_f32_e32 v4, v56, v56
	v_add_f32_e32 v3, v3, v4
	v_add_f32_e32 v2, v2, v3
	v_mul_f32_e32 v3, v51, v51
	v_mul_f32_e32 v4, v53, v53
	v_fmac_f32_e32 v3, v50, v50
	v_fmac_f32_e32 v4, v52, v52
	v_add_f32_e32 v3, v3, v4
	v_add_f32_e32 v2, v3, v2
	v_mov_b32_e32 v3, v2
	s_nop 1
	v_permlane16_swap_b32_e32 v2, v3
	v_add_f32_e32 v2, v2, v3
	v_mov_b32_e32 v3, v2
	s_nop 1
	v_permlane32_swap_b32_e32 v2, v3
	s_and_saveexec_b64 s[10:11], vcc
	s_lshl_b32 s7, s44, 10
	s_add_i32 s7, s6, s7
	v_add_f32_e32 v2, v2, v3
	v_lshl_add_u32 v3, v164, 4, s7
	ds_write_b32 v3, v2 offset:512
	s_or_b64 exec, exec, s[10:11]
	v_mul_f32_e32 v2, v111, v111
	v_mul_f32_e32 v3, v113, v113
	v_fmac_f32_e32 v2, v110, v110
	v_fmac_f32_e32 v3, v112, v112
	v_add_f32_e32 v2, v2, v3
	v_mul_f32_e32 v3, v107, v107
	v_mul_f32_e32 v4, v109, v109
	v_fmac_f32_e32 v3, v106, v106
	v_fmac_f32_e32 v4, v108, v108
	v_add_f32_e32 v3, v3, v4
	v_add_f32_e32 v2, v3, v2
	v_mul_f32_e32 v3, v47, v47
	v_mul_f32_e32 v4, v49, v49
	v_fmac_f32_e32 v3, v46, v46
	v_fmac_f32_e32 v4, v48, v48
	v_add_f32_e32 v3, v3, v4
	v_add_f32_e32 v2, v2, v3
	v_mul_f32_e32 v3, v43, v43
	v_mul_f32_e32 v4, v45, v45
	v_fmac_f32_e32 v3, v42, v42
	v_fmac_f32_e32 v4, v44, v44
	v_add_f32_e32 v3, v3, v4
	v_add_f32_e32 v2, v3, v2
	v_mov_b32_e32 v3, v2
	s_nop 1
	v_permlane16_swap_b32_e32 v2, v3
	v_add_f32_e32 v2, v2, v3
	v_mov_b32_e32 v3, v2
	s_nop 1
	v_permlane32_swap_b32_e32 v2, v3
	s_and_saveexec_b64 s[10:11], vcc
	s_lshl_b32 s7, s44, 10
	s_add_i32 s7, s6, s7
	v_add_f32_e32 v2, v2, v3
	v_lshl_add_u32 v3, v164, 4, s7
	ds_write_b32 v3, v2 offset:768
	s_or_b64 exec, exec, s[10:11]
	v_mul_f32_e32 v2, v103, v103
	v_mul_f32_e32 v3, v105, v105
	v_fmac_f32_e32 v2, v102, v102
	v_fmac_f32_e32 v3, v104, v104
	v_add_f32_e32 v2, v2, v3
	v_mul_f32_e32 v3, v99, v99
	v_mul_f32_e32 v4, v101, v101
	v_fmac_f32_e32 v3, v98, v98
	v_fmac_f32_e32 v4, v100, v100
	v_add_f32_e32 v3, v3, v4
	v_add_f32_e32 v2, v3, v2
	v_mul_f32_e32 v3, v39, v39
	v_mul_f32_e32 v4, v41, v41
	v_fmac_f32_e32 v3, v38, v38
	v_fmac_f32_e32 v4, v40, v40
	v_add_f32_e32 v3, v3, v4
	v_add_f32_e32 v2, v2, v3
	v_mul_f32_e32 v3, v35, v35
	v_mul_f32_e32 v4, v37, v37
	v_fmac_f32_e32 v3, v34, v34
	v_fmac_f32_e32 v4, v36, v36
	v_add_f32_e32 v3, v3, v4
	v_add_f32_e32 v2, v3, v2
	v_mov_b32_e32 v3, v2
	s_nop 1
	v_permlane16_swap_b32_e32 v2, v3
	v_add_f32_e32 v2, v2, v3
	v_mov_b32_e32 v3, v2
	s_nop 1
	v_permlane32_swap_b32_e32 v2, v3
	s_and_saveexec_b64 s[10:11], vcc
	s_lshl_b32 s7, s44, 10
	s_add_i32 s7, s6, s7
	v_add_f32_e32 v2, v2, v3
	v_lshl_add_u32 v3, v164, 4, s7
	ds_write_b32 v3, v2 offset:2048
	s_or_b64 exec, exec, s[10:11]
	v_mul_f32_e32 v2, v95, v95
	v_mul_f32_e32 v3, v97, v97
	v_fmac_f32_e32 v2, v94, v94
	v_fmac_f32_e32 v3, v96, v96
	v_add_f32_e32 v2, v2, v3
	v_mul_f32_e32 v3, v91, v91
	v_mul_f32_e32 v4, v93, v93
	v_fmac_f32_e32 v3, v90, v90
	v_fmac_f32_e32 v4, v92, v92
	v_add_f32_e32 v3, v3, v4
	v_add_f32_e32 v2, v3, v2
	v_mul_f32_e32 v3, v31, v31
	v_mul_f32_e32 v4, v33, v33
	v_fmac_f32_e32 v3, v30, v30
	v_fmac_f32_e32 v4, v32, v32
	v_add_f32_e32 v3, v3, v4
	v_add_f32_e32 v2, v2, v3
	v_mul_f32_e32 v3, v27, v27
	v_mul_f32_e32 v4, v29, v29
	v_fmac_f32_e32 v3, v26, v26
	v_fmac_f32_e32 v4, v28, v28
	v_add_f32_e32 v3, v3, v4
	v_add_f32_e32 v2, v3, v2
	v_mov_b32_e32 v3, v2
	s_nop 1
	v_permlane16_swap_b32_e32 v2, v3
	v_add_f32_e32 v2, v2, v3
	v_mov_b32_e32 v3, v2
	s_nop 1
	v_permlane32_swap_b32_e32 v2, v3
	s_and_saveexec_b64 s[10:11], vcc
	s_lshl_b32 s7, s44, 10
	s_add_i32 s7, s6, s7
	v_add_f32_e32 v2, v2, v3
	v_lshl_add_u32 v3, v164, 4, s7
	ds_write_b32 v3, v2 offset:2304
	s_or_b64 exec, exec, s[10:11]
	v_mul_f32_e32 v2, v87, v87
	v_mul_f32_e32 v3, v89, v89
	v_fmac_f32_e32 v2, v86, v86
	v_fmac_f32_e32 v3, v88, v88
	v_add_f32_e32 v2, v2, v3
	v_mul_f32_e32 v3, v83, v83
	v_mul_f32_e32 v4, v85, v85
	v_fmac_f32_e32 v3, v82, v82
	v_fmac_f32_e32 v4, v84, v84
	v_add_f32_e32 v3, v3, v4
	v_add_f32_e32 v2, v3, v2
	v_mul_f32_e32 v3, v79, v79
	v_mul_f32_e32 v4, v77, v77
	v_fmac_f32_e32 v3, v78, v78
	v_fmac_f32_e32 v4, v76, v76
	v_add_f32_e32 v3, v3, v4
	v_add_f32_e32 v2, v2, v3
	v_mul_f32_e32 v3, v81, v81
	v_mul_f32_e32 v4, v75, v75
	v_fmac_f32_e32 v3, v80, v80
	v_fmac_f32_e32 v4, v74, v74
	v_add_f32_e32 v3, v3, v4
	v_add_f32_e32 v2, v3, v2
	v_mov_b32_e32 v3, v2
	s_nop 1
	v_permlane16_swap_b32_e32 v2, v3
	v_add_f32_e32 v2, v2, v3
	v_mov_b32_e32 v3, v2
	s_nop 1
	v_permlane32_swap_b32_e32 v2, v3
	s_and_saveexec_b64 s[10:11], vcc
	s_lshl_b32 s7, s44, 10
	s_add_i32 s7, s6, s7
	v_add_f32_e32 v2, v2, v3
	v_lshl_add_u32 v3, v164, 4, s7
	ds_write_b32 v3, v2 offset:2560
	s_or_b64 exec, exec, s[10:11]
	v_mul_f32_e32 v2, v143, v143
	v_mul_f32_e32 v3, v141, v141
	v_fmac_f32_e32 v2, v142, v142
	v_fmac_f32_e32 v3, v140, v140
	v_add_f32_e32 v2, v2, v3
	v_mul_f32_e32 v3, v145, v145
	v_mul_f32_e32 v4, v139, v139
	v_fmac_f32_e32 v3, v144, v144
	v_fmac_f32_e32 v4, v138, v138
	v_add_f32_e32 v3, v3, v4
	v_add_f32_e32 v2, v3, v2
	v_mul_f32_e32 v3, v155, v155
	v_mul_f32_e32 v4, v153, v153
	v_fmac_f32_e32 v3, v154, v154
	v_fmac_f32_e32 v4, v152, v152
	v_add_f32_e32 v3, v3, v4
	v_add_f32_e32 v2, v2, v3
	v_mul_f32_e32 v3, v157, v157
	v_mul_f32_e32 v4, v147, v147
	v_fmac_f32_e32 v3, v156, v156
	v_fmac_f32_e32 v4, v146, v146
	v_add_f32_e32 v3, v3, v4
	v_add_f32_e32 v2, v3, v2
	v_mov_b32_e32 v3, v2
	s_nop 1
	v_permlane16_swap_b32_e32 v2, v3
	v_add_f32_e32 v2, v2, v3
	v_mov_b32_e32 v3, v2
	s_nop 1
	v_permlane32_swap_b32_e32 v2, v3
	s_and_saveexec_b64 s[10:11], vcc
	s_lshl_b32 s7, s44, 10
	s_add_i32 s6, s6, s7
	v_add_f32_e32 v2, v2, v3
	v_lshl_add_u32 v3, v164, 4, s6
	ds_write_b32 v3, v2 offset:2816
	s_or_b64 exec, exec, s[10:11]
	s_waitcnt lgkmcnt(0)
	s_barrier
	v_cmp_gt_u32_e32 vcc, 32, v0
	s_and_saveexec_b64 s[34:35], vcc
	s_cbranch_execz .LBB0_903
	v_and_b32_e32 v0, 31, v163
	v_lshl_or_b32 v4, s29, 5, v0
	v_lshl_add_u32 v0, v4, 4, 0
	ds_read_b128 v[6:9], v0
	s_lshl_b64 s[6:7], s[24:25], 18
	s_add_u32 s6, s18, s6
	s_addc_u32 s7, s19, s7
	s_ashr_i32 s29, s28, 31
	s_waitcnt lgkmcnt(0)
	v_mov_b32_e32 v2, v7
	v_mov_b32_e32 v3, v8
	v_mov_b32_e32 v7, v9
	v_pk_add_f32 v[2:3], v[2:3], v[6:7]
	s_cmp_eq_u32 s28, 0
	v_add_f32_e32 v2, v2, v3
	v_max_f32_e32 v5, 0xda24260, v2
	v_add_u32_e32 v2, s70, v4
	v_ashrrev_i32_e32 v3, 31, v2
	v_lshl_add_u64 v[2:3], v[2:3], 4, s[6:7]
	s_mov_b64 s[6:7], 0xf540000
	v_lshl_add_u64 v[2:3], v[2:3], 0, s[6:7]
	v_lshl_add_u64 v[6:7], s[28:29], 2, v[2:3]
	global_store_dword v[6:7], v5, off sc1
	s_cselect_b64 s[10:11], -1, 0
	s_cmp_lg_u32 s28, 1
	s_cselect_b64 s[24:25], -1, 0
	s_cmp_lg_u32 s28, 2
	s_cselect_b64 s[38:39], -1, 0
	s_cmp_lg_u32 s28, 3
	s_cselect_b64 s[40:41], -1, 0
	s_mov_b32 s12, 0
	global_load_dwordx4 v[228:231], v[2:3], off sc1
	s_sleep 15
.Lrs_loop:
	global_load_dwordx4 v[232:235], v[2:3], off sc1
	s_waitcnt vmcnt(1)
	v_cmp_eq_u32_e32 vcc, 0, v228
	s_andn2_b64 s[6:7], vcc, s[10:11]
	v_cmp_eq_u32_e32 vcc, 0, v229
	s_and_b64 s[42:43], vcc, s[24:25]
	s_or_b64 s[6:7], s[6:7], s[42:43]
	v_cmp_eq_u32_e32 vcc, 0, v230
	s_and_b64 s[42:43], vcc, s[38:39]
	s_or_b64 s[6:7], s[6:7], s[42:43]
	v_cmp_eq_u32_e32 vcc, 0, v231
	s_and_b64 s[42:43], vcc, s[40:41]
	s_or_b64 s[6:7], s[6:7], s[42:43]
	s_cmp_eq_u64 s[6:7], 0
	s_cbranch_scc1 .Lrs_doneA
	global_load_dwordx4 v[228:231], v[2:3], off sc1
	s_waitcnt vmcnt(1)
	v_cmp_eq_u32_e32 vcc, 0, v232
	s_andn2_b64 s[6:7], vcc, s[10:11]
	v_cmp_eq_u32_e32 vcc, 0, v233
	s_and_b64 s[42:43], vcc, s[24:25]
	s_or_b64 s[6:7], s[6:7], s[42:43]
	v_cmp_eq_u32_e32 vcc, 0, v234
	s_and_b64 s[42:43], vcc, s[38:39]
	s_or_b64 s[6:7], s[6:7], s[42:43]
	v_cmp_eq_u32_e32 vcc, 0, v235
	s_and_b64 s[42:43], vcc, s[40:41]
	s_or_b64 s[6:7], s[6:7], s[42:43]
	s_cmp_eq_u64 s[6:7], 0
	s_cbranch_scc1 .Lrs_doneB
	s_add_i32 s12, s12, 1
	s_cmpk_lt_u32 s12, 0x4000
	s_cbranch_scc1 .Lrs_loop
	s_waitcnt vmcnt(0)
.Lrs_doneB:
	v_mov_b32_e32 v9, v232
	v_mov_b32_e32 v6, v233
	v_mov_b32_e32 v8, v234
	v_mov_b32_e32 v7, v235
	s_branch .Lrs_done
.Lrs_doneA:
	v_mov_b32_e32 v9, v228
	v_mov_b32_e32 v6, v229
	v_mov_b32_e32 v8, v230
	v_mov_b32_e32 v7, v231
.Lrs_done:
.LBB0_902:
	s_cmp_eq_u32 s28, 1
	s_cselect_b64 vcc, -1, 0
	s_cmp_eq_u32 s28, 3
	s_waitcnt lgkmcnt(0)
	s_cselect_b64 s[12:13], -1, 0
	s_cmp_eq_u32 s28, 2
	v_cndmask_b32_e64 v2, v9, v5, s[10:11]
	s_cselect_b64 s[10:11], -1, 0
	v_cndmask_b32_e64 v3, v8, v5, s[10:11]
	v_cndmask_b32_e64 v7, v7, v5, s[12:13]
	v_cndmask_b32_e32 v6, v6, v5, vcc
	v_pk_add_f32 v[2:3], v[2:3], v[6:7]
	s_mov_b32 s45, 0x12000
	v_add_f32_e32 v2, v2, v3
	v_fmamk_f32 v2, v2, 0x3a800000, v218
	v_mul_f32_e32 v3, 0x4b800000, v2
	v_cmp_gt_f32_e32 vcc, s86, v2
	s_mov_b32 s38, 0x63000
	s_mov_b32 s39, 0xc6000
	v_cndmask_b32_e32 v2, v2, v3, vcc
	v_rsq_f32_e32 v2, v2
	s_nop 0
	v_mul_f32_e32 v3, 0x45800000, v2
	v_cndmask_b32_e32 v5, v2, v3, vcc
	v_mad_u64_u32 v[2:3], s[6:7], v4, -12, v[0:1]
	ds_write_b32 v2, v5 offset:4096
